# gdn_prep item loop rotated: next item's conv-input loads issued before the current item's record stores; item-top wait vmcnt(5) instead of full drain
# baseline (speedup 1.0000x reference)
; #define LDSBAR() do { asm volatile("s_waitcnt lgkmcnt(0)" ::: "memory"); __builtin_amdgcn_s_barrier(); asm volatile("" ::: "memory"); } while (0)
; DI void gdn_prep_item(const Args& a, int l, int bh, int n, LAS unsigned char* lds, const int tidx, const int xf) {
;     ...
;     const float av = ab[(row0 + (tid & 63)) * 12 + h], bv = ab[(row0 + (tid & 63)) * 12 + 6 + h];
;     {
;         const int t = tid >> 3, cgp = tid & 7, tpos = n * 64 + t;
;         u32x4 raw[3][4][2];
; #pragma unroll
;         for (int sec = 0; sec < 3; ++sec)
; #pragma unroll
;             for (int tap = 0; tap < 4; ++tap) { const bool ok = (tpos - 3 + tap >= 0);
;                 const bf16_t* p = proj + (row0 + t - (ok ? 3 - tap : 0)) * NPROJ + C_GQ + sec * 768 + h * 128 + cgp * 16;
;                 raw[sec][tap][0] = *(const u32x4*)p; raw[sec][tap][1] = *(const u32x4*)(p + 8); }
;     ...
;     LDSBAR();
; #pragma unroll
;     for (int rep = 0; rep < 2; ++rep) {
.LBB0_394:
	s_or_b64 exec, exec, s[22:23]
	v_add_u32_e32 v142, v96, v191
	v_mov_b32_e32 v144, v48
	s_waitcnt lgkmcnt(0)
	s_barrier
	s_add_i32 s35, s35, s48
	s_cmpk_gt_i32 s35, 0x5ff
	s_cbranch_scc1 .Lprep_nopf
	s_ashr_i32 s4, s35, 6
	s_mul_hi_i32 s22, s4, 0x2aaaaaab
	s_lshr_b32 s23, s22, 31
	s_add_i32 s22, s22, s23
	s_mul_i32 s23, s22, 6
	s_and_b32 s5, s35, 63
	s_sub_i32 s82, s4, s23
	s_ashr_i32 s23, s22, 31
	s_lshl_b64 s[22:23], s[22:23], 12
	s_lshl_b32 s4, s5, 6
	s_or_b32 s22, s22, s4
	v_add_u32_e32 v197, s4, v162
	v_or_b32_e32 v0, s22, v160
	v_cmp_gt_i32_e32 vcc, 3, v197
	v_mad_u64_u32 v[0:1], s[24:25], v0, 48, s[36:37]
	v_lshl_add_u64 v[2:3], s[22:23], 0, v[162:163]
	v_cndmask_b32_e64 v5, -1, 0, vcc
	v_cndmask_b32_e64 v4, -3, 0, vcc
	s_lshl_b32 s24, s82, 7
	v_lshl_add_u64 v[4:5], v[2:3], 0, v[4:5]
	v_mov_b64_e32 v[6:7], s[58:59]
	v_mad_i32_i24 v1, s23, 48, v1
	s_ashr_i32 s25, s24, 31
	v_mad_u64_u32 v[8:9], s[22:23], v4, s47, v[6:7]
	v_mad_i32_i24 v9, v5, s47, v9
	s_lshl_b64 s[26:27], s[24:25], 1
	v_lshlrev_b32_e32 v204, 1, v164
	v_lshl_add_u64 v[4:5], v[8:9], 0, s[26:27]
	v_lshl_add_u64 v[4:5], v[4:5], 0, v[204:205]
	s_mov_b32 s4, 0x7d02000
	v_add_co_u32_e32 v10, vcc, s4, v4
	s_ashr_i32 s83, s82, 31
	s_nop 0
	v_addc_co_u32_e32 v11, vcc, 0, v5, vcc
	v_lshl_add_u64 v[0:1], s[82:83], 2, v[0:1]
	s_mov_b64 s[30:31], 0x7d02400
	v_cmp_gt_i32_e32 vcc, 2, v197
	v_mov_b32 v194, 0
	v_lshl_add_u64 v[8:9], v[4:5], 0, s[30:31]
	global_load_dword v196, v[0:1], off
	global_load_dword v195, v[0:1], off offset:24
	global_load_dwordx4 v[64:67], v[8:9], off offset:16
	v_cndmask_b32_e64 v1, -1, 0, vcc
	v_cndmask_b32_e64 v0, -2, 0, vcc
	v_lshl_add_u64 v[0:1], v[2:3], 0, v[0:1]
	v_mad_u64_u32 v[8:9], s[22:23], v0, s47, v[6:7]
	v_mad_i32_i24 v9, v1, s47, v9
	v_lshl_add_u64 v[0:1], v[8:9], 0, s[26:27]
	v_lshl_add_u64 v[0:1], v[0:1], 0, v[204:205]
	v_add_co_u32_e32 v12, vcc, s4, v0
	v_lshl_add_u64 v[8:9], v[0:1], 0, s[30:31]
	s_nop 0
	v_addc_co_u32_e32 v13, vcc, 0, v1, vcc
	v_cmp_lt_i32_e64 s[22:23], 0, v197
	global_load_dwordx4 v[92:95], v[12:13], off offset:1024
	global_load_dwordx4 v[68:71], v[8:9], off offset:16
	v_cndmask_b32_e64 v8, 0, 1, s[22:23]
	v_sub_co_u32_e32 v8, vcc, v2, v8
	v_mad_u64_u32 v[8:9], s[28:29], v8, s47, v[6:7]
	s_nop 0
	v_subbrev_co_u32_e32 v14, vcc, 0, v3, vcc
	v_mad_i32_i24 v9, v14, s47, v9
	v_lshl_add_u64 v[8:9], v[8:9], 0, s[26:27]
	v_mad_u64_u32 v[6:7], s[28:29], v2, s47, v[6:7]
	v_lshl_add_u64 v[8:9], v[8:9], 0, v[204:205]
	v_mad_i32_i24 v7, v3, s47, v7
	v_add_co_u32_e32 v16, vcc, s4, v8
	v_lshl_add_u64 v[2:3], v[6:7], 0, s[26:27]
	s_nop 0
	v_addc_co_u32_e32 v17, vcc, 0, v9, vcc
	v_lshl_add_u64 v[28:29], v[2:3], 0, v[204:205]
	v_add_co_u32_e32 v6, vcc, s4, v28
	s_mov_b64 s[26:27], 0x7d02a00
	s_nop 0
	v_addc_co_u32_e32 v7, vcc, 0, v29, vcc
	v_lshl_add_u64 v[14:15], v[8:9], 0, s[30:31]
	v_lshl_add_u64 v[2:3], v[28:29], 0, s[30:31]
	global_load_dwordx4 v[96:99], v[6:7], off offset:1024
	global_load_dwordx4 v[72:75], v[2:3], off offset:16
	global_load_dwordx4 v[104:107], v[10:11], off offset:1024
	global_load_dwordx4 v[60:63], v[10:11], off offset:2560
	v_lshl_add_u64 v[10:11], v[0:1], 0, s[26:27]
	v_lshl_add_u64 v[2:3], v[4:5], 0, s[26:27]
	global_load_dwordx4 v[76:79], v[14:15], off offset:16
	global_load_dwordx4 v[56:59], v[12:13], off offset:2560
	v_lshl_add_u64 v[12:13], v[8:9], 0, s[26:27]
	global_load_dwordx4 v[100:103], v[16:17], off offset:1024
	global_load_dwordx4 v[52:55], v[16:17], off offset:2560
	global_load_dwordx4 v[40:43], v[10:11], off offset:16
	global_load_dwordx4 v[32:35], v[12:13], off offset:16
	v_lshl_add_u64 v[10:11], v[28:29], 0, s[26:27]
	s_mov_b64 s[26:27], 0x7d03000
	s_mov_b32 s4, 0x7d03000
	global_load_dwordx4 v[44:47], v[2:3], off offset:16
	global_load_dwordx4 v[48:51], v[6:7], off offset:2560
	v_lshl_add_u64 v[2:3], v[4:5], 0, s[26:27]
	v_add_co_u32_e32 v4, vcc, s4, v4
	global_load_dwordx4 v[36:39], v[10:11], off offset:16
	global_load_dwordx4 v[16:19], v[2:3], off offset:16
	v_addc_co_u32_e32 v5, vcc, 0, v5, vcc
	v_add_co_u32_e32 v10, vcc, s4, v0
	v_lshl_add_u64 v[12:13], v[8:9], 0, s[26:27]
	s_nop 0
	v_addc_co_u32_e32 v11, vcc, 0, v1, vcc
	v_add_co_u32_e32 v14, vcc, s4, v8
	v_lshl_add_u64 v[6:7], v[0:1], 0, s[26:27]
	s_nop 0
	v_addc_co_u32_e32 v15, vcc, 0, v9, vcc
	v_add_co_u32_e32 v8, vcc, s4, v28
	v_lshl_add_u64 v[30:31], v[28:29], 0, s[26:27]
	s_nop 0
	v_addc_co_u32_e32 v9, vcc, 0, v29, vcc
	global_load_dwordx4 v[0:3], v[4:5], off
	global_load_dwordx4 v[20:23], v[6:7], off offset:16
	s_nop 0
	global_load_dwordx4 v[4:7], v[10:11], off
	global_load_dwordx4 v[24:27], v[12:13], off offset:16
	s_nop 0
	global_load_dwordx4 v[8:11], v[8:9], off
	s_nop 0
	global_load_dwordx4 v[12:15], v[14:15], off
	s_nop 0
	global_load_dwordx4 v[28:31], v[30:31], off offset:16
; #define LDSBAR() do { asm volatile("s_waitcnt lgkmcnt(0)" ::: "memory"); __builtin_amdgcn_s_barrier(); asm volatile("" ::: "memory"); } while (0)
; DI void gdn_prep_item(const Args& a, int l, int bh, int n, LAS unsigned char* lds, const int tidx, const int xf) {
;     ...
; #pragma unroll
;     for (int rep = 0; rep < 2; ++rep) {
;         const int idx = tid + 512 * rep, fl = idx & 63, fs = (idx >> 6) & 7, fmt = idx >> 9;
;         const int row = fmt * 32 + (fl & 31), c0 = 16 * fs + 4 * (fl >> 5);
;         const bf16x8 w = lds_cvt8(ks + row * QS_LD + c0, ks + row * QS_LD + c0 + 8, 1.f);
;         const bf16x8 q = lds_cvt8(qs + row * QS_LD + c0, qs + row * QS_LD + c0 + 8, egs[row]);
;         *(bf16x8*)(rec + (size_t)idx * 16) = w;
;         *(bf16x8*)(rec + 16384 + (size_t)idx * 16) = q;
;     }
;     {
;         const int idx = tid, fl = idx & 63, fs = (idx >> 6) & 3, fmt = idx >> 8;
;         const int row = fmt * 32 + (fl & 31), c0 = 16 * fs + 4 * (fl >> 5);
;         *(bf16x8*)(rec + 49152 + (size_t)idx * 16) = lds_cvt8(Ai + row * MM_LD + c0, Ai + row * MM_LD + c0 + 8, 1.f);
;     }
;     LDSBAR();
; __global__ void __launch_bounds__(512, 2) hybrid_fwd(Args a0) {
;     ...
;             if (!(a0.repmask & 16)) for (int it = bx; it < BATCH * NH * 64; it += G) gdn_prep_item(a, l, it >> 6, it & 63, lds, tl, a0.repmask);
.Lprep_nopf:
	v_add_u32_e32 v132, v142, v192
	ds_read_b128 v[128:131], v132
	ds_read_b128 v[132:135], v132 offset:32
	v_add_u32_e32 v143, v194, v191
	v_add_u32_e32 v136, v143, v192
	s_mov_b32 s98, 0x15500000
	s_waitcnt lgkmcnt(1)
	v_cvt_pk_bf16_f32 v128, v128, v129
	v_cvt_pk_bf16_f32 v129, v130, v131
	s_waitcnt lgkmcnt(0)
	v_cvt_pk_bf16_f32 v130, v132, v133
	v_lshl_add_u32 v132, v186, 2, v194
	v_cvt_pk_bf16_f32 v131, v134, v135
	ds_read_b32 v140, v132 offset:35840
	ds_read_b128 v[132:135], v136 offset:36096
	ds_read_b128 v[136:139], v136 offset:36128
	s_mov_b32 s99, 0x15504000
	v_readlane_b32 s100, v254, 11
	s_waitcnt lgkmcnt(1)
	v_pk_mul_f32 v[132:133], v[140:141], v[132:133] op_sel_hi:[0,1]
	v_pk_mul_f32 v[134:135], v[140:141], v[134:135] op_sel_hi:[0,1]
	s_waitcnt lgkmcnt(0)
	v_pk_mul_f32 v[136:137], v[140:141], v[136:137] op_sel_hi:[0,1]
	v_pk_mul_f32 v[138:139], v[140:141], v[138:139] op_sel_hi:[0,1]
	v_lshl_add_u64 v[140:141], v[166:167], 0, s[94:95]
	v_cvt_pk_bf16_f32 v132, v132, v133
	v_cvt_pk_bf16_f32 v133, v134, v135
	v_cvt_pk_bf16_f32 v134, v136, v137
	v_add_co_u32_e32 v136, vcc, s98, v140
	v_cvt_pk_bf16_f32 v135, v138, v139
	s_nop 0
	v_addc_co_u32_e32 v137, vcc, 0, v141, vcc
	global_store_dwordx4 v[136:137], v[128:131], off
	v_add_u32_e32 v136, v143, v193
	v_readlane_b32 s101, v254, 12
	v_add_co_u32_e32 v128, vcc, s99, v140
	s_nop 0
	v_lshl_add_u64 v[170:171], v[170:171], 0, s[100:101]
	v_addc_co_u32_e32 v129, vcc, 0, v141, vcc
	global_store_dwordx4 v[128:129], v[132:135], off
	s_nop 1
	v_add_u32_e32 v132, v142, v193
	ds_read_b128 v[128:131], v132
	ds_read_b128 v[132:135], v132 offset:32
	s_waitcnt lgkmcnt(1)
	v_cvt_pk_bf16_f32 v128, v128, v129
	v_cvt_pk_bf16_f32 v129, v130, v131
	s_waitcnt lgkmcnt(0)
	v_cvt_pk_bf16_f32 v130, v132, v133
	v_lshl_add_u32 v132, v187, 2, v194
	v_cvt_pk_bf16_f32 v131, v134, v135
	ds_read_b32 v142, v132 offset:35840
	ds_read_b128 v[132:135], v136 offset:36096
	ds_read_b128 v[136:139], v136 offset:36128
	s_waitcnt lgkmcnt(1)
	v_pk_mul_f32 v[132:133], v[142:143], v[132:133] op_sel_hi:[0,1]
	v_pk_mul_f32 v[134:135], v[142:143], v[134:135] op_sel_hi:[0,1]
	s_waitcnt lgkmcnt(0)
	v_pk_mul_f32 v[136:137], v[142:143], v[136:137] op_sel_hi:[0,1]
	v_pk_mul_f32 v[138:139], v[142:143], v[138:139] op_sel_hi:[0,1]
	v_cvt_pk_bf16_f32 v132, v132, v133
	v_cvt_pk_bf16_f32 v133, v134, v135
	v_cvt_pk_bf16_f32 v134, v136, v137
	v_lshl_add_u64 v[136:137], v[168:169], 0, s[94:95]
	v_cvt_pk_bf16_f32 v135, v138, v139
	v_add_co_u32_e32 v138, vcc, s98, v136
	s_mov_b32 s98, 0x1550c000
	s_nop 0
	v_addc_co_u32_e32 v139, vcc, 0, v137, vcc
	global_store_dwordx4 v[138:139], v[128:131], off
	s_nop 1
	v_add_co_u32_e32 v128, vcc, s99, v136
	s_nop 1
	v_addc_co_u32_e32 v129, vcc, 0, v137, vcc
	global_store_dwordx4 v[128:129], v[132:135], off
	v_add_u32_e32 v128, v194, v188
	s_nop 0
	v_add3_u32 v132, v128, v189, v144
	ds_read_b128 v[128:131], v132 offset:17408
	ds_read_b128 v[132:135], v132 offset:17440
	s_waitcnt lgkmcnt(1)
	v_cvt_pk_bf16_f32 v128, v128, v129
	v_cvt_pk_bf16_f32 v129, v130, v131
	s_waitcnt lgkmcnt(0)
	v_cvt_pk_bf16_f32 v130, v132, v133
	v_add_co_u32_e32 v132, vcc, s98, v140
	v_cvt_pk_bf16_f32 v131, v134, v135
	s_nop 0
	v_addc_co_u32_e32 v133, vcc, 0, v141, vcc
	v_readlane_b32 s98, v254, 7
	global_store_dwordx4 v[132:133], v[128:131], off
	v_readlane_b32 s99, v254, 8
	s_add_u32 s91, s91, s98
	s_waitcnt lgkmcnt(0)
	s_barrier
	s_addc_u32 s34, s34, s99
	v_readlane_b32 s98, v254, 1
	v_readlane_b32 s99, v254, 2
	s_cmpk_gt_i32 s35, 0x5ff
	s_nop 0
	v_lshl_add_u64 v[166:167], v[166:167], 0, s[98:99]
	v_lshl_add_u64 v[168:169], v[168:169], 0, s[98:99]
	v_lshl_add_u64 v[172:173], v[172:173], 0, s[98:99]
	s_cbranch_scc1 .LBB0_490
	s_waitcnt vmcnt(5)
	s_branch .Lprep_join
; DI void gdn_prep_item(const Args& a, int l, int bh, int n, LAS unsigned char* lds, const int tidx, const int xf) {
;     ...
;     const float av = ab[(row0 + (tid & 63)) * 12 + h], bv = ab[(row0 + (tid & 63)) * 12 + 6 + h];
;     {
;         const int t = tid >> 3, cgp = tid & 7, tpos = n * 64 + t;
;         u32x4 raw[3][4][2];
; #pragma unroll
;         for (int sec = 0; sec < 3; ++sec)
; #pragma unroll
;             for (int tap = 0; tap < 4; ++tap) { const bool ok = (tpos - 3 + tap >= 0);
;                 const bf16_t* p = proj + (row0 + t - (ok ? 3 - tap : 0)) * NPROJ + C_GQ + sec * 768 + h * 128 + cgp * 16;
;                 raw[sec][tap][0] = *(const u32x4*)p; raw[sec][tap][1] = *(const u32x4*)(p + 8); }
;     ...
;             for (int tap = 0; tap < 4; ++tap) {
;                 const bool ok = (tpos - 3 + tap >= 0);
;                 const f32x4* wp = (const f32x4*)(convw + tap * 2304 + wbase);
; #pragma unroll
;                 for (int c4 = 0; c4 < 4; ++c4) wv[tap][c4] = wp[c4];
;                 if (n == 0) { const float m = ok ? 1.f : 0.f;
; #pragma unroll
;                     for (int c4 = 0; c4 < 4; ++c4) wv[tap][c4] = wv[tap][c4] * m; }
.LBB0_395:
	s_ashr_i32 s4, s35, 6
	s_mul_hi_i32 s22, s4, 0x2aaaaaab
	s_lshr_b32 s23, s22, 31
	s_add_i32 s22, s22, s23
	s_mul_i32 s23, s22, 6
	s_and_b32 s5, s35, 63
	s_sub_i32 s82, s4, s23
	s_ashr_i32 s23, s22, 31
	s_lshl_b64 s[22:23], s[22:23], 12
	s_lshl_b32 s4, s5, 6
	s_or_b32 s22, s22, s4
	v_add_u32_e32 v197, s4, v162
	v_or_b32_e32 v0, s22, v160
	v_cmp_gt_i32_e32 vcc, 3, v197
	v_mad_u64_u32 v[0:1], s[24:25], v0, 48, s[36:37]
	v_lshl_add_u64 v[2:3], s[22:23], 0, v[162:163]
	v_cndmask_b32_e64 v5, -1, 0, vcc
	v_cndmask_b32_e64 v4, -3, 0, vcc
	s_lshl_b32 s24, s82, 7
	v_lshl_add_u64 v[4:5], v[2:3], 0, v[4:5]
	v_mov_b64_e32 v[6:7], s[58:59]
	v_mad_i32_i24 v1, s23, 48, v1
	s_ashr_i32 s25, s24, 31
	v_mad_u64_u32 v[8:9], s[22:23], v4, s47, v[6:7]
	v_mad_i32_i24 v9, v5, s47, v9
	s_lshl_b64 s[26:27], s[24:25], 1
	v_lshlrev_b32_e32 v204, 1, v164
	v_lshl_add_u64 v[4:5], v[8:9], 0, s[26:27]
	v_lshl_add_u64 v[4:5], v[4:5], 0, v[204:205]
	s_mov_b32 s4, 0x7d02000
	v_add_co_u32_e32 v10, vcc, s4, v4
	s_ashr_i32 s83, s82, 31
	s_nop 0
	v_addc_co_u32_e32 v11, vcc, 0, v5, vcc
	v_lshl_add_u64 v[0:1], s[82:83], 2, v[0:1]
	s_mov_b64 s[30:31], 0x7d02400
	v_cmp_gt_i32_e32 vcc, 2, v197
	v_mov_b32 v194, 0
	v_lshl_add_u64 v[8:9], v[4:5], 0, s[30:31]
	global_load_dword v196, v[0:1], off
	global_load_dword v195, v[0:1], off offset:24
	global_load_dwordx4 v[64:67], v[8:9], off offset:16
	v_cndmask_b32_e64 v1, -1, 0, vcc
	v_cndmask_b32_e64 v0, -2, 0, vcc
	v_lshl_add_u64 v[0:1], v[2:3], 0, v[0:1]
	v_mad_u64_u32 v[8:9], s[22:23], v0, s47, v[6:7]
	v_mad_i32_i24 v9, v1, s47, v9
	v_lshl_add_u64 v[0:1], v[8:9], 0, s[26:27]
	v_lshl_add_u64 v[0:1], v[0:1], 0, v[204:205]
	v_add_co_u32_e32 v12, vcc, s4, v0
	v_lshl_add_u64 v[8:9], v[0:1], 0, s[30:31]
	s_nop 0
	v_addc_co_u32_e32 v13, vcc, 0, v1, vcc
	v_cmp_lt_i32_e64 s[22:23], 0, v197
	global_load_dwordx4 v[92:95], v[12:13], off offset:1024
	global_load_dwordx4 v[68:71], v[8:9], off offset:16
	v_cndmask_b32_e64 v8, 0, 1, s[22:23]
	v_sub_co_u32_e32 v8, vcc, v2, v8
	v_mad_u64_u32 v[8:9], s[28:29], v8, s47, v[6:7]
	s_nop 0
	v_subbrev_co_u32_e32 v14, vcc, 0, v3, vcc
	v_mad_i32_i24 v9, v14, s47, v9
	v_lshl_add_u64 v[8:9], v[8:9], 0, s[26:27]
	v_mad_u64_u32 v[6:7], s[28:29], v2, s47, v[6:7]
	v_lshl_add_u64 v[8:9], v[8:9], 0, v[204:205]
	v_mad_i32_i24 v7, v3, s47, v7
	v_add_co_u32_e32 v16, vcc, s4, v8
	v_lshl_add_u64 v[2:3], v[6:7], 0, s[26:27]
	s_nop 0
	v_addc_co_u32_e32 v17, vcc, 0, v9, vcc
	v_lshl_add_u64 v[28:29], v[2:3], 0, v[204:205]
	v_add_co_u32_e32 v6, vcc, s4, v28
	s_mov_b64 s[26:27], 0x7d02a00
	s_nop 0
	v_addc_co_u32_e32 v7, vcc, 0, v29, vcc
	v_lshl_add_u64 v[14:15], v[8:9], 0, s[30:31]
	v_lshl_add_u64 v[2:3], v[28:29], 0, s[30:31]
	global_load_dwordx4 v[96:99], v[6:7], off offset:1024
	global_load_dwordx4 v[72:75], v[2:3], off offset:16
	global_load_dwordx4 v[104:107], v[10:11], off offset:1024
	global_load_dwordx4 v[60:63], v[10:11], off offset:2560
	v_lshl_add_u64 v[10:11], v[0:1], 0, s[26:27]
	v_lshl_add_u64 v[2:3], v[4:5], 0, s[26:27]
	global_load_dwordx4 v[76:79], v[14:15], off offset:16
	global_load_dwordx4 v[56:59], v[12:13], off offset:2560
	v_lshl_add_u64 v[12:13], v[8:9], 0, s[26:27]
	global_load_dwordx4 v[100:103], v[16:17], off offset:1024
	global_load_dwordx4 v[52:55], v[16:17], off offset:2560
	global_load_dwordx4 v[40:43], v[10:11], off offset:16
	global_load_dwordx4 v[32:35], v[12:13], off offset:16
	v_lshl_add_u64 v[10:11], v[28:29], 0, s[26:27]
	s_mov_b64 s[26:27], 0x7d03000
	s_mov_b32 s4, 0x7d03000
	global_load_dwordx4 v[44:47], v[2:3], off offset:16
	global_load_dwordx4 v[48:51], v[6:7], off offset:2560
	v_lshl_add_u64 v[2:3], v[4:5], 0, s[26:27]
	v_add_co_u32_e32 v4, vcc, s4, v4
	global_load_dwordx4 v[36:39], v[10:11], off offset:16
	global_load_dwordx4 v[16:19], v[2:3], off offset:16
	v_addc_co_u32_e32 v5, vcc, 0, v5, vcc
	v_add_co_u32_e32 v10, vcc, s4, v0
	v_lshl_add_u64 v[12:13], v[8:9], 0, s[26:27]
	s_nop 0
	v_addc_co_u32_e32 v11, vcc, 0, v1, vcc
	v_add_co_u32_e32 v14, vcc, s4, v8
	v_lshl_add_u64 v[6:7], v[0:1], 0, s[26:27]
	s_nop 0
	v_addc_co_u32_e32 v15, vcc, 0, v9, vcc
	v_add_co_u32_e32 v8, vcc, s4, v28
	v_lshl_add_u64 v[30:31], v[28:29], 0, s[26:27]
	s_nop 0
	v_addc_co_u32_e32 v9, vcc, 0, v29, vcc
	global_load_dwordx4 v[0:3], v[4:5], off
	global_load_dwordx4 v[20:23], v[6:7], off offset:16
	s_nop 0
	global_load_dwordx4 v[4:7], v[10:11], off
	global_load_dwordx4 v[24:27], v[12:13], off offset:16
	s_nop 0
	global_load_dwordx4 v[8:11], v[8:9], off
	s_nop 0
	global_load_dwordx4 v[12:15], v[14:15], off
	s_nop 0
	global_load_dwordx4 v[28:31], v[30:31], off offset:16
	s_waitcnt vmcnt(0)
.Lprep_join:
	v_or_b32_e32 v80, s24, v164
	v_ashrrev_i32_e32 v81, 31, v80
	v_lshl_add_u64 v[174:175], v[80:81], 2, s[0:1]
	global_load_dwordx4 v[144:147], v[174:175], off offset:48
	global_load_dwordx4 v[80:83], v[174:175], off offset:32
	global_load_dwordx4 v[112:115], v[174:175], off offset:16
	global_load_dwordx4 v[128:131], v[174:175], off
	s_cmp_eq_u32 s5, 0
	s_cselect_b64 s[28:29], -1, 0
	s_cmp_lg_u32 s5, 0
	v_cmp_lt_i32_e64 s[26:27], 2, v197
	s_cbranch_scc1 .LBB0_397
	s_waitcnt vmcnt(36)
	v_cndmask_b32_e64 v84, 0, 1.0, s[26:27]
	s_waitcnt vmcnt(0)
	v_pk_mul_f32 v[130:131], v[84:85], v[130:131] op_sel_hi:[0,1]
	v_pk_mul_f32 v[128:129], v[84:85], v[128:129] op_sel_hi:[0,1]
	v_pk_mul_f32 v[114:115], v[84:85], v[114:115] op_sel_hi:[0,1]
	v_pk_mul_f32 v[112:113], v[84:85], v[112:113] op_sel_hi:[0,1]
	v_pk_mul_f32 v[82:83], v[84:85], v[82:83] op_sel_hi:[0,1]
	v_pk_mul_f32 v[80:81], v[84:85], v[80:81] op_sel_hi:[0,1]
	v_pk_mul_f32 v[146:147], v[84:85], v[146:147] op_sel_hi:[0,1]
	v_pk_mul_f32 v[144:145], v[84:85], v[144:145] op_sel_hi:[0,1]
